# mixc: stats loop keeps 12 loads in flight per iteration; spatial-gating epilogue issues all 40 loads before the read-modify-write instead of one round trip per element
# speedup vs baseline: 1.0507x; 1.0461x over previous
; DI float bf2f(u16 v) { return __uint_as_float(((unsigned)v) << 16); }
; DI void phase_mixc(const Prm& p, unsigned char* smem_raw, int l, int& base) {
;     ...
;       const int q = tid & 127, qf = tid >> 7;
;       float s = 0.f, ss = 0.f;
;       const u16* src = p.cvT + (size_t)(qf * 96) * TBP + tok0 + q;
;       for (int c = 0; c < 96; ++c) { const float v = bf2f(src[(size_t)c * TBP]); s += v; ss += v * v; }
;       red[qf * 256 + q * 2] = s; red[qf * 256 + q * 2 + 1] = ss;
;       __syncthreads();
;       if (tid < 128) {
;         const float s1 = red[q * 2] + red[256 + q * 2] + red[512 + q * 2] + red[768 + q * 2];
;         const float s2 = red[q * 2 + 1] + red[256 + q * 2 + 1] + red[512 + q * 2 + 1] + red[768 + q * 2 + 1];
;         const float mu = s1 * (1.f / 384.f);
;         const float var = fmaxf(s2 * (1.f / 384.f) - mu * mu, 0.f);
;         st[q] = mu; st[128 + q] = rsqrtf(var + 1e-6f);
;       }
;       __syncthreads();
.LBB0_2003:
	v_lshl_add_u64 v[4:5], v[2:3], 0, s[2:3]
	global_load_ushort v10, v[4:5], off
	s_mov_b32 s4, 0x20000
	s_add_u32 s2, s2, 0x60600
	s_addc_u32 s3, s3, 0
	s_cmp_eq_u32 s2, 0x303000
	v_add_co_u32_e32 v8, vcc, 0x8000, v4
	s_nop 1
	v_addc_co_u32_e32 v9, vcc, 0, v5, vcc
	global_load_ushort v11, v[8:9], off offset:128
	v_add_co_u32_e32 v8, vcc, s90, v4
	s_nop 1
	v_addc_co_u32_e32 v9, vcc, 0, v5, vcc
	global_load_ushort v12, v[8:9], off offset:256
	v_add_co_u32_e32 v8, vcc, s75, v4
	s_nop 1
	v_addc_co_u32_e32 v9, vcc, 0, v5, vcc
	global_load_ushort v13, v[8:9], off offset:384
	v_add_co_u32_e32 v8, vcc, s4, v4
	s_mov_b32 s4, 0x28000
	s_nop 0
	v_addc_co_u32_e32 v9, vcc, 0, v5, vcc
	global_load_ushort v14, v[8:9], off offset:512
	v_add_co_u32_e32 v8, vcc, s4, v4
	s_mov_b32 s4, 0x38000
	s_nop 0
	v_addc_co_u32_e32 v9, vcc, 0, v5, vcc
	global_load_ushort v15, v[8:9], off offset:640
	v_add_co_u32_e32 v8, vcc, s5, v4
	s_nop 1
	v_addc_co_u32_e32 v9, vcc, 0, v5, vcc
	global_load_ushort v16, v[8:9], off offset:768
	v_add_co_u32_e32 v8, vcc, s4, v4
	s_mov_b32 s4, 0x40000
	s_nop 0
	v_addc_co_u32_e32 v9, vcc, 0, v5, vcc
	global_load_ushort v17, v[8:9], off offset:896
	v_add_co_u32_e32 v8, vcc, s4, v4
	s_mov_b32 s4, 0x48000
	s_nop 0
	v_addc_co_u32_e32 v9, vcc, 0, v5, vcc
	global_load_ushort v18, v[8:9], off offset:1024
	v_add_co_u32_e32 v8, vcc, s4, v4
	s_mov_b32 s4, 0x50000
	s_nop 0
	v_addc_co_u32_e32 v9, vcc, 0, v5, vcc
	global_load_ushort v19, v[8:9], off offset:1152
	v_add_co_u32_e32 v8, vcc, s4, v4
	s_mov_b32 s4, 0x58000
	s_nop 0
	v_addc_co_u32_e32 v9, vcc, 0, v5, vcc
	global_load_ushort v20, v[8:9], off offset:1280
	v_add_co_u32_e32 v4, vcc, s4, v4
	s_nop 1
	v_addc_co_u32_e32 v5, vcc, 0, v5, vcc
	global_load_ushort v21, v[4:5], off offset:1408
	s_waitcnt vmcnt(0)
	v_lshlrev_b32_e32 v8, 16, v10
	v_mul_f32_e32 v9, v8, v8
	v_pk_add_f32 v[6:7], v[6:7], v[8:9]
	v_lshlrev_b32_e32 v8, 16, v11
	v_mul_f32_e32 v9, v8, v8
	v_pk_add_f32 v[6:7], v[6:7], v[8:9]
	v_lshlrev_b32_e32 v8, 16, v12
	v_mul_f32_e32 v9, v8, v8
	v_pk_add_f32 v[6:7], v[6:7], v[8:9]
	v_lshlrev_b32_e32 v8, 16, v13
	v_mul_f32_e32 v9, v8, v8
	v_pk_add_f32 v[6:7], v[6:7], v[8:9]
	v_lshlrev_b32_e32 v8, 16, v14
	v_mul_f32_e32 v9, v8, v8
	v_pk_add_f32 v[6:7], v[6:7], v[8:9]
	v_lshlrev_b32_e32 v8, 16, v15
	v_mul_f32_e32 v9, v8, v8
	v_pk_add_f32 v[6:7], v[6:7], v[8:9]
	v_lshlrev_b32_e32 v8, 16, v16
	v_mul_f32_e32 v9, v8, v8
	v_pk_add_f32 v[6:7], v[6:7], v[8:9]
	v_lshlrev_b32_e32 v8, 16, v17
	v_mul_f32_e32 v9, v8, v8
	v_pk_add_f32 v[6:7], v[6:7], v[8:9]
	v_lshlrev_b32_e32 v8, 16, v18
	v_mul_f32_e32 v9, v8, v8
	v_pk_add_f32 v[6:7], v[6:7], v[8:9]
	v_lshlrev_b32_e32 v8, 16, v19
	v_mul_f32_e32 v9, v8, v8
	v_pk_add_f32 v[6:7], v[6:7], v[8:9]
	v_lshlrev_b32_e32 v8, 16, v20
	v_mul_f32_e32 v9, v8, v8
	v_pk_add_f32 v[6:7], v[6:7], v[8:9]
	v_lshlrev_b32_e32 v8, 16, v21
	v_mul_f32_e32 v9, v8, v8
	v_pk_add_f32 v[6:7], v[6:7], v[8:9]
	s_cbranch_scc0 .LBB0_2003
	ds_write_b64 v59, v[6:7]
	s_waitcnt lgkmcnt(0)
	s_barrier
	s_and_saveexec_b64 s[2:3], s[0:1]
	s_cbranch_execz .LBB0_2006
	ds_read2st64_b64 v[2:5], v58 offset1:2
	s_mov_b32 s4, 0x3b2aaaab
	s_waitcnt lgkmcnt(0)
	v_pk_add_f32 v[6:7], v[2:3], v[4:5]
	ds_read2st64_b64 v[2:5], v58 offset0:4 offset1:6
	s_waitcnt lgkmcnt(0)
	v_pk_add_f32 v[2:3], v[6:7], v[2:3]
	s_nop 0
	v_pk_add_f32 v[2:3], v[2:3], v[4:5]
	s_nop 0
	v_pk_mul_f32 v[2:3], v[2:3], s[4:5] op_sel_hi:[1,0]
	s_nop 0
	v_fma_f32 v0, -v2, v2, v3
	v_max_f32_e32 v0, 0, v0
	v_add_f32_e32 v0, 0x358637bd, v0
	v_cmp_gt_f32_e32 vcc, s85, v0
	v_mul_f32_e32 v3, 0x4b800000, v0
	s_nop 0
	v_cndmask_b32_e32 v0, v0, v3, vcc
	v_rsq_f32_e32 v0, v0
	s_nop 0
	v_mul_f32_e32 v3, 0x45800000, v0
	v_cndmask_b32_e32 v0, v0, v3, vcc
	ds_write2st64_b32 v60, v2, v0 offset1:2

; DI float bf2f(u16 v) { return __uint_as_float(((unsigned)v) << 16); }
; DI int rowmap(int r, int lh) { return (r & 3) + 8 * (r >> 2) + 4 * lh; }
; DI f32x16 mfma(bf16x8 a, bf16x8 b, f32x16 c) { return __builtin_amdgcn_mfma_f32_32x32x16_bf16(a, b, c, 0, 0, 0); }
; template <bool RFA, bool RFB, class LA, class LB, class EPI>
; DI void gemm_tile(u16* smem, int nk, LA la, LB lb, EPI epi) {
;     ...
;   for (int kt = 0; kt < nk; ++kt) {
;     const int buf = kt & 1;
;     if (kt + 1 < nk) {
;       const int k0 = (kt + 1) * 64;
; #pragma unroll
;       for (int i = 0; i < 2; ++i) { const int c = tid + NTH * i; ra[i] = la(A_ROW(c), k0 + A_KC(c) * 8); rb[i] = lb(B_ROW(c), k0 + B_KC(c) * 8); }
;     }
;     const u16* Ab = As + buf * TILE_ELEMS + (wm * 64 + lr) * LDT + lh * 8;
;     const u16* Bb = Bs + buf * TILE_ELEMS + (wn * 32 + lr) * LDT + lh * 8;
; #pragma unroll
;     for (int ks = 0; ks < 4; ++ks) {
;       const bf16x8 a0 = *(const bf16x8*)(Ab + ks * 16);
;       const bf16x8 a1 = *(const bf16x8*)(Ab + 32 * LDT + ks * 16);
;       const bf16x8 b = *(const bf16x8*)(Bb + ks * 16);
;       acc[0] = mfma(a0, b, acc[0]);
;       acc[1] = mfma(a1, b, acc[1]);
;     }
;     if (kt + 1 < nk) {
;       u16* Aw = As + (buf ^ 1) * TILE_ELEMS;
;       u16* Bw = Bs + (buf ^ 1) * TILE_ELEMS;
; #pragma unroll
;       for (int i = 0; i < 2; ++i) {
;         const int c = tid + NTH * i;
;         *(u32x4*)(Aw + A_ROW(c) * LDT + A_KC(c) * 8) = ra[i];
;         *(u32x4*)(Bw + B_ROW(c) * LDT + B_KC(c) * 8) = rb[i];
;       }
;     }
;     __syncthreads();
;   }
; DI void phase_mixc(const Prm& p, unsigned char* smem_raw, int l, int& base) {
;     ...
;     auto epi = [&](f32x16 (&acc)[2], int wm, int wn, int lane) __attribute__((always_inline)) {
;       const int lr = lane & 31, lh = lane >> 5;
;       const int cl = wn * 32 + lr;
;       if (cl < 96) {
; #pragma unroll
;         for (int i = 0; i < 2; ++i)
; #pragma unroll
;           for (int r = 0; r < 16; ++r) {
;             const int pp = wm * 64 + i * 32 + rowmap(r, lh);
;             const float val = acc[i][r] + p.sgu_b[(l * 4 + h) * 128 + pp];
;     ...
;             *dst = f2bf(bf2f(*dst) * val);
.LBB0_2014:
	s_or_b64 exec, exec, s[6:7]
	v_ashrrev_i32_e32 v0, 2, v53
	v_and_b32_e32 v6, 31, v53
	v_and_b32_e32 v52, 0xffffffc0, v0
	v_lshrrev_b32_e32 v0, 1, v53
	v_or_b32_e32 v2, v52, v6
	v_and_b32_e32 v0, 16, v0
	v_mad_u64_u32 v[70:71], s[2:3], v2, s70, v[0:1]
	ds_read_b128 v[2:5], v70
	v_bfe_u32 v57, v53, 6, 2
	v_lshl_or_b32 v55, v57, 5, v6
	v_mad_u32_u24 v0, v55, s70, v0
	ds_read_b128 v[6:9], v0 offset:36864
	s_waitcnt lgkmcnt(0)
	v_mfma_f32_32x32x16_bf16 v[18:33], v[2:5], v[6:9], 0
	ds_read_b128 v[2:5], v70 offset:4608
	ds_read_b128 v[62:65], v70 offset:32
	ds_read_b128 v[66:69], v0 offset:36896
	v_cmp_ne_u32_e32 vcc, 3, v57
	s_waitcnt lgkmcnt(0)
	v_mfma_f32_32x32x16_bf16 v[18:33], v[62:65], v[66:69], v[18:33]
	ds_read_b128 v[62:65], v70 offset:4640
	v_mfma_f32_32x32x16_bf16 v[2:17], v[2:5], v[6:9], 0
	s_waitcnt lgkmcnt(0)
	v_mfma_f32_32x32x16_bf16 v[2:17], v[62:65], v[66:69], v[2:17]
	ds_read_b128 v[62:65], v70 offset:64
	ds_read_b128 v[66:69], v0 offset:36928
	s_waitcnt lgkmcnt(0)
	v_mfma_f32_32x32x16_bf16 v[18:33], v[62:65], v[66:69], v[18:33]
	ds_read_b128 v[62:65], v70 offset:4672
	s_waitcnt lgkmcnt(0)
	v_mfma_f32_32x32x16_bf16 v[2:17], v[62:65], v[66:69], v[2:17]
	ds_read_b128 v[62:65], v70 offset:96
	ds_read_b128 v[66:69], v0 offset:36960
	s_waitcnt lgkmcnt(0)
	v_mfma_f32_32x32x16_bf16 v[18:33], v[62:65], v[66:69], v[18:33]
	ds_read_b128 v[62:65], v70 offset:4704
	s_waitcnt vmcnt(1)
	ds_write_b128 v54, v[34:37] offset:18432
	ds_write_b128 v54, v[42:45] offset:55296
	s_waitcnt vmcnt(0)
	ds_write_b128 v56, v[46:49] offset:18432
	ds_write_b128 v56, v[38:41] offset:55296
	s_waitcnt lgkmcnt(0)
	s_barrier
	ds_read_b128 v[34:37], v70 offset:18432
	ds_read_b128 v[38:41], v0 offset:55296
	s_waitcnt lgkmcnt(0)
	v_mfma_f32_32x32x16_bf16 v[18:33], v[34:37], v[38:41], v[18:33]
	ds_read_b128 v[34:37], v70 offset:23040
	v_mfma_f32_32x32x16_bf16 v[2:17], v[62:65], v[66:69], v[2:17]
	s_waitcnt lgkmcnt(0)
	v_mfma_f32_32x32x16_bf16 v[2:17], v[34:37], v[38:41], v[2:17]
	ds_read_b128 v[34:37], v70 offset:18464
	ds_read_b128 v[38:41], v0 offset:55328
	s_waitcnt lgkmcnt(0)
	v_mfma_f32_32x32x16_bf16 v[18:33], v[34:37], v[38:41], v[18:33]
	ds_read_b128 v[34:37], v70 offset:23072
	s_waitcnt lgkmcnt(0)
	v_mfma_f32_32x32x16_bf16 v[2:17], v[34:37], v[38:41], v[2:17]
	ds_read_b128 v[34:37], v70 offset:18496
	ds_read_b128 v[38:41], v0 offset:55360
	s_waitcnt lgkmcnt(0)
	v_mfma_f32_32x32x16_bf16 v[18:33], v[34:37], v[38:41], v[18:33]
	ds_read_b128 v[34:37], v70 offset:23104
	s_waitcnt lgkmcnt(0)
	v_mfma_f32_32x32x16_bf16 v[2:17], v[34:37], v[38:41], v[2:17]
	ds_read_b128 v[34:37], v70 offset:18528
	ds_read_b128 v[38:41], v0 offset:55392
	s_waitcnt lgkmcnt(0)
	v_mfma_f32_32x32x16_bf16 v[18:33], v[34:37], v[38:41], v[18:33]
	ds_read_b128 v[34:37], v70 offset:23136
	s_waitcnt lgkmcnt(0)
	s_barrier
	v_mfma_f32_32x32x16_bf16 v[2:17], v[34:37], v[38:41], v[2:17]
	s_and_saveexec_b64 s[2:3], vcc
	s_cbranch_execz .LBB0_2001
	v_lshrrev_b32_e32 v0, 3, v53
	v_and_b32_e32 v36, 4, v0
	v_mul_u32_u24_e32 v0, s55, v240
	v_readlane_b32 s36, v253, 24
	v_lshlrev_b32_e32 v0, 1, v0
	v_readlane_b32 s42, v253, 30
	v_readlane_b32 s43, v253, 31
	v_readlane_b32 s37, v253, 25
	v_readlane_b32 s38, v253, 26
	v_lshl_add_u64 v[34:35], s[42:43], 0, v[0:1]
	v_lshlrev_b32_e32 v0, 1, v55
	v_readlane_b32 s39, v253, 27
	v_readlane_b32 s40, v253, 28
	v_readlane_b32 s41, v253, 29
	v_readlane_b32 s44, v253, 32
	v_readlane_b32 s45, v253, 33
	v_readlane_b32 s46, v253, 34
	v_readlane_b32 s47, v253, 35
	v_readlane_b32 s48, v253, 36
	v_readlane_b32 s49, v253, 37
	v_readlane_b32 s50, v253, 38
	v_readlane_b32 s51, v253, 39
	v_lshl_add_u64 v[34:35], v[34:35], 0, v[0:1]
	v_or_b32_e32 v0, v36, v52
	v_add_u32_e32 v38, s66, v0
	v_readlane_b32 s36, v252, 8
	v_ashrrev_i32_e32 v39, 31, v38
	v_readlane_b32 s37, v252, 9
	v_add_u32_e32 v0, s4, v0
	v_lshl_add_u64 v[38:39], v[38:39], 2, s[36:37]
	global_load_dwordx4 v[96:99], v[38:39], off
	global_load_dwordx4 v[100:103], v[38:39], off offset:32
	global_load_dwordx4 v[104:107], v[38:39], off offset:64
	global_load_dwordx4 v[108:111], v[38:39], off offset:96
	global_load_dwordx4 v[112:115], v[38:39], off offset:128
	global_load_dwordx4 v[116:119], v[38:39], off offset:160
	global_load_dwordx4 v[120:123], v[38:39], off offset:192
	global_load_dwordx4 v[124:127], v[38:39], off offset:224
	v_mov_b32_e32 v72, v0
	v_mad_i64_i32 v[80:81], s[6:7], v72, s33, v[34:35]
	global_load_ushort v128, v[80:81], off
	global_load_ushort v129, v[80:81], off offset:768
	global_load_ushort v130, v[80:81], off offset:1536
	global_load_ushort v131, v[80:81], off offset:2304
	v_add_u32_e32 v72, 8, v0
	v_mad_i64_i32 v[82:83], s[6:7], v72, s33, v[34:35]
	global_load_ushort v132, v[82:83], off
	global_load_ushort v133, v[82:83], off offset:768
	global_load_ushort v134, v[82:83], off offset:1536
	global_load_ushort v135, v[82:83], off offset:2304
	v_add_u32_e32 v72, 16, v0
	v_mad_i64_i32 v[84:85], s[6:7], v72, s33, v[34:35]
	global_load_ushort v136, v[84:85], off
	global_load_ushort v137, v[84:85], off offset:768
	global_load_ushort v138, v[84:85], off offset:1536
	global_load_ushort v139, v[84:85], off offset:2304
	v_add_u32_e32 v72, 24, v0
	v_mad_i64_i32 v[86:87], s[6:7], v72, s33, v[34:35]
	global_load_ushort v140, v[86:87], off
	global_load_ushort v141, v[86:87], off offset:768
	global_load_ushort v142, v[86:87], off offset:1536
	global_load_ushort v143, v[86:87], off offset:2304
	v_add_u32_e32 v72, 32, v0
	v_mad_i64_i32 v[88:89], s[6:7], v72, s33, v[34:35]
	global_load_ushort v144, v[88:89], off
	global_load_ushort v145, v[88:89], off offset:768
	global_load_ushort v146, v[88:89], off offset:1536
	global_load_ushort v147, v[88:89], off offset:2304
	v_add_u32_e32 v72, 40, v0
	v_mad_i64_i32 v[90:91], s[6:7], v72, s33, v[34:35]
	global_load_ushort v148, v[90:91], off
	global_load_ushort v149, v[90:91], off offset:768
	global_load_ushort v150, v[90:91], off offset:1536
	global_load_ushort v151, v[90:91], off offset:2304
	v_add_u32_e32 v72, 48, v0
	v_mad_i64_i32 v[92:93], s[6:7], v72, s33, v[34:35]
	global_load_ushort v152, v[92:93], off
	global_load_ushort v153, v[92:93], off offset:768
	global_load_ushort v154, v[92:93], off offset:1536
	global_load_ushort v155, v[92:93], off offset:2304
	v_add_u32_e32 v72, 56, v0
	v_mad_i64_i32 v[94:95], s[6:7], v72, s33, v[34:35]
	global_load_ushort v156, v[94:95], off
	global_load_ushort v157, v[94:95], off offset:768
	global_load_ushort v158, v[94:95], off offset:1536
	global_load_ushort v159, v[94:95], off offset:2304
	v_readlane_b32 s38, v252, 10
	v_readlane_b32 s39, v252, 11
	v_readlane_b32 s40, v252, 12
	v_readlane_b32 s41, v252, 13
	v_readlane_b32 s42, v252, 14
	v_readlane_b32 s43, v252, 15
	v_readlane_b32 s44, v252, 16
	v_readlane_b32 s45, v252, 17
	v_readlane_b32 s46, v252, 18
	v_readlane_b32 s47, v252, 19
	v_readlane_b32 s48, v252, 20
	v_readlane_b32 s49, v252, 21
	v_readlane_b32 s50, v252, 22
	v_readlane_b32 s51, v252, 23
	s_waitcnt vmcnt(0)
; DI float bf2f(u16 v) { return __uint_as_float(((unsigned)v) << 16); }
; DI int rowmap(int r, int lh) { return (r & 3) + 8 * (r >> 2) + 4 * lh; }
; DI void phase_mixc(const Prm& p, unsigned char* smem_raw, int l, int& base) {
;     ...
;       if (cl < 96) {
; #pragma unroll
;         for (int i = 0; i < 2; ++i)
; #pragma unroll
;           for (int r = 0; r < 16; ++r) {
;             const int pp = wm * 64 + i * 32 + rowmap(r, lh);
;             const float val = acc[i][r] + p.sgu_b[(l * 4 + h) * 128 + pp];
;     ...
;             *dst = f2bf(bf2f(*dst) * val);
;           }
	v_add_f32_e32 v18, v18, v96
	v_lshlrev_b32_e32 v128, 16, v128
	v_mul_f32_e32 v128, v18, v128
	v_cvt_pk_bf16_f32 v128, v128, v128
	global_store_short v[80:81], v128, off
	v_add_f32_e32 v19, v19, v97
	v_lshlrev_b32_e32 v129, 16, v129
	v_mul_f32_e32 v129, v19, v129
	v_cvt_pk_bf16_f32 v129, v129, v129
	global_store_short v[80:81], v129, off offset:768
	v_add_f32_e32 v20, v20, v98
	v_lshlrev_b32_e32 v130, 16, v130
	v_mul_f32_e32 v130, v20, v130
	v_cvt_pk_bf16_f32 v130, v130, v130
	global_store_short v[80:81], v130, off offset:1536
	v_add_f32_e32 v21, v21, v99
	v_lshlrev_b32_e32 v131, 16, v131
	v_mul_f32_e32 v131, v21, v131
	v_cvt_pk_bf16_f32 v131, v131, v131
	global_store_short v[80:81], v131, off offset:2304
	v_add_f32_e32 v22, v22, v100
	v_lshlrev_b32_e32 v132, 16, v132
	v_mul_f32_e32 v132, v22, v132
	v_cvt_pk_bf16_f32 v132, v132, v132
	global_store_short v[82:83], v132, off
	v_add_f32_e32 v23, v23, v101
	v_lshlrev_b32_e32 v133, 16, v133
	v_mul_f32_e32 v133, v23, v133
	v_cvt_pk_bf16_f32 v133, v133, v133
	global_store_short v[82:83], v133, off offset:768
	v_add_f32_e32 v24, v24, v102
	v_lshlrev_b32_e32 v134, 16, v134
	v_mul_f32_e32 v134, v24, v134
	v_cvt_pk_bf16_f32 v134, v134, v134
	global_store_short v[82:83], v134, off offset:1536
	v_add_f32_e32 v25, v25, v103
	v_lshlrev_b32_e32 v135, 16, v135
	v_mul_f32_e32 v135, v25, v135
	v_cvt_pk_bf16_f32 v135, v135, v135
	global_store_short v[82:83], v135, off offset:2304
	v_add_f32_e32 v26, v26, v104
	v_lshlrev_b32_e32 v136, 16, v136
	v_mul_f32_e32 v136, v26, v136
	v_cvt_pk_bf16_f32 v136, v136, v136
	global_store_short v[84:85], v136, off
	v_add_f32_e32 v27, v27, v105
	v_lshlrev_b32_e32 v137, 16, v137
	v_mul_f32_e32 v137, v27, v137
	v_cvt_pk_bf16_f32 v137, v137, v137
	global_store_short v[84:85], v137, off offset:768
	v_add_f32_e32 v28, v28, v106
	v_lshlrev_b32_e32 v138, 16, v138
	v_mul_f32_e32 v138, v28, v138
	v_cvt_pk_bf16_f32 v138, v138, v138
	global_store_short v[84:85], v138, off offset:1536
	v_add_f32_e32 v29, v29, v107
	v_lshlrev_b32_e32 v139, 16, v139
	v_mul_f32_e32 v139, v29, v139
	v_cvt_pk_bf16_f32 v139, v139, v139
	global_store_short v[84:85], v139, off offset:2304
	v_add_f32_e32 v30, v30, v108
	v_lshlrev_b32_e32 v140, 16, v140
	v_mul_f32_e32 v140, v30, v140
	v_cvt_pk_bf16_f32 v140, v140, v140
	global_store_short v[86:87], v140, off
	v_add_f32_e32 v31, v31, v109
	v_lshlrev_b32_e32 v141, 16, v141
	v_mul_f32_e32 v141, v31, v141
	v_cvt_pk_bf16_f32 v141, v141, v141
	global_store_short v[86:87], v141, off offset:768
	v_add_f32_e32 v32, v32, v110
	v_lshlrev_b32_e32 v142, 16, v142
	v_mul_f32_e32 v142, v32, v142
	v_cvt_pk_bf16_f32 v142, v142, v142
	global_store_short v[86:87], v142, off offset:1536
	v_add_f32_e32 v33, v33, v111
	v_lshlrev_b32_e32 v143, 16, v143
	v_mul_f32_e32 v143, v33, v143
	v_cvt_pk_bf16_f32 v143, v143, v143
	global_store_short v[86:87], v143, off offset:2304
	v_add_f32_e32 v2, v2, v112
	v_lshlrev_b32_e32 v144, 16, v144
	v_mul_f32_e32 v144, v2, v144
	v_cvt_pk_bf16_f32 v144, v144, v144
	global_store_short v[88:89], v144, off
	v_add_f32_e32 v3, v3, v113
	v_lshlrev_b32_e32 v145, 16, v145
	v_mul_f32_e32 v145, v3, v145
	v_cvt_pk_bf16_f32 v145, v145, v145
	global_store_short v[88:89], v145, off offset:768
	v_add_f32_e32 v4, v4, v114
	v_lshlrev_b32_e32 v146, 16, v146
	v_mul_f32_e32 v146, v4, v146
	v_cvt_pk_bf16_f32 v146, v146, v146
	global_store_short v[88:89], v146, off offset:1536
	v_add_f32_e32 v5, v5, v115
	v_lshlrev_b32_e32 v147, 16, v147
	v_mul_f32_e32 v147, v5, v147
	v_cvt_pk_bf16_f32 v147, v147, v147
	global_store_short v[88:89], v147, off offset:2304
	v_add_f32_e32 v6, v6, v116
	v_lshlrev_b32_e32 v148, 16, v148
	v_mul_f32_e32 v148, v6, v148
	v_cvt_pk_bf16_f32 v148, v148, v148
	global_store_short v[90:91], v148, off
	v_add_f32_e32 v7, v7, v117
	v_lshlrev_b32_e32 v149, 16, v149
	v_mul_f32_e32 v149, v7, v149
	v_cvt_pk_bf16_f32 v149, v149, v149
	global_store_short v[90:91], v149, off offset:768
	v_add_f32_e32 v8, v8, v118
	v_lshlrev_b32_e32 v150, 16, v150
	v_mul_f32_e32 v150, v8, v150
	v_cvt_pk_bf16_f32 v150, v150, v150
	global_store_short v[90:91], v150, off offset:1536
	v_add_f32_e32 v9, v9, v119
	v_lshlrev_b32_e32 v151, 16, v151
	v_mul_f32_e32 v151, v9, v151
	v_cvt_pk_bf16_f32 v151, v151, v151
	global_store_short v[90:91], v151, off offset:2304
	v_add_f32_e32 v10, v10, v120
	v_lshlrev_b32_e32 v152, 16, v152
	v_mul_f32_e32 v152, v10, v152
	v_cvt_pk_bf16_f32 v152, v152, v152
	global_store_short v[92:93], v152, off
	v_add_f32_e32 v11, v11, v121
	v_lshlrev_b32_e32 v153, 16, v153
	v_mul_f32_e32 v153, v11, v153
	v_cvt_pk_bf16_f32 v153, v153, v153
	global_store_short v[92:93], v153, off offset:768
	v_add_f32_e32 v12, v12, v122
	v_lshlrev_b32_e32 v154, 16, v154
	v_mul_f32_e32 v154, v12, v154
	v_cvt_pk_bf16_f32 v154, v154, v154
	global_store_short v[92:93], v154, off offset:1536
	v_add_f32_e32 v13, v13, v123
	v_lshlrev_b32_e32 v155, 16, v155
	v_mul_f32_e32 v155, v13, v155
	v_cvt_pk_bf16_f32 v155, v155, v155
	global_store_short v[92:93], v155, off offset:2304
	v_add_f32_e32 v14, v14, v124
	v_lshlrev_b32_e32 v156, 16, v156
	v_mul_f32_e32 v156, v14, v156
	v_cvt_pk_bf16_f32 v156, v156, v156
	global_store_short v[94:95], v156, off
	v_add_f32_e32 v15, v15, v125
	v_lshlrev_b32_e32 v157, 16, v157
	v_mul_f32_e32 v157, v15, v157
	v_cvt_pk_bf16_f32 v157, v157, v157
	global_store_short v[94:95], v157, off offset:768
	v_add_f32_e32 v16, v16, v126
	v_lshlrev_b32_e32 v158, 16, v158
	v_mul_f32_e32 v158, v16, v158
	v_cvt_pk_bf16_f32 v158, v158, v158
	global_store_short v[94:95], v158, off offset:1536
	v_add_f32_e32 v17, v17, v127
	v_lshlrev_b32_e32 v159, 16, v159
	v_mul_f32_e32 v159, v17, v159
	v_cvt_pk_bf16_f32 v159, v159, v159
	global_store_short v[94:95], v159, off offset:2304
	s_branch .LBB0_2001
